# GDN phase 1: parallel prefix-sum for chunk decays and fully prefetched f32/bf16 MFMA operands on compute waves
# speedup vs baseline: 1.0072x; 1.0072x over previous
; #define LAS __attribute__((address_space(3)))
; DI unsigned pk2(float lo, float hi) { f32x2 v = {lo, hi}; bf16x2_t b = __builtin_convertvector(v, bf16x2_t); return __builtin_bit_cast(unsigned, b); }
; #define MFMA16F(a, b, c) __builtin_amdgcn_mfma_f32_16x16x4f32((a), (b), (c), 0, 0, 0)
; DI void gdn_scan_block(LAS unsigned char* lds, int c, const float* P, const GdnPar& pr, float* ORAW, int tid, int lane, int wave) {
;     ...
;         if (wave < 4) {
; #pragma unroll
;             for (int tb = 0; tb < 2; ++tb) { P0a[tb] = (f32x4){0.f, 0.f, 0.f, 0.f}; PQa[tb] = P0a[tb]; }
; #pragma unroll
;             for (int kb8 = 0; kb8 < 8; ++kb8)
; #pragma unroll
;                 for (int i = 0; i < 4; ++i) { const float bS = Sacc[kb8][i];
; #pragma unroll
;                     for (int tb = 0; tb < 2; ++tb) { const int off = (16 * tb + m) * KP + 16 * kb8 + 4 * g + i;
;                         P0a[tb] = MFMA16F(K_[off], bS, P0a[tb]); } }
; #pragma unroll
;             for (int ks = 0; ks < 4; ++ks) {
;                 u32x4 w; w.x = pk2(Sacc[2 * ks][0], Sacc[2 * ks][1]); w.y = pk2(Sacc[2 * ks][2], Sacc[2 * ks][3]); w.z = pk2(Sacc[2 * ks + 1][0], Sacc[2 * ks + 1][1]); w.w = pk2(Sacc[2 * ks + 1][2], Sacc[2 * ks + 1][3]);
;                 const bf16x8 bSb = __builtin_bit_cast(bf16x8, w);
; #pragma unroll
;                 for (int tb = 0; tb < 2; ++tb) { const LAS unsigned char* qp = QB + ((16 * tb + m) * 136 + 32 * ks + 4 * g) * 2;
;                     const s16x4 lo = *(const LAS s16x4*)qp, hi = *(const LAS s16x4*)(qp + 32);
;                     PQa[tb] = __builtin_amdgcn_mfma_f32_16x16x32_bf16(__builtin_shufflevector(lo, hi, 0, 1, 2, 3, 4, 5, 6, 7), bSb, PQa[tb], 0, 0, 0); } }
.LBB0_903:
	v_add_u32_e32 v80, 0x1000, v175
	ds_read2_b64 v[236:239], v175 offset0:0 offset1:4
	ds_read2_b64 v[250:253], v80 offset0:32 offset1:36
	ds_read2_b64 v[246:249], v175 offset0:8 offset1:12
	ds_read2_b64 v[100:103], v80 offset0:40 offset1:44
	ds_read_b128 v[190:193], v174 offset:16896
	ds_read_b128 v[194:197], v174 offset:25344
	ds_read_b128 v[198:201], v174 offset:16960
	ds_read_b128 v[202:205], v174 offset:25408
	ds_read_b128 v[208:211], v174 offset:17024
	ds_read_b128 v[212:215], v174 offset:25472
	ds_read_b128 v[216:219], v174 offset:17088
	ds_read_b128 v[220:223], v174 offset:25536
	ds_read_b128 v[224:227], v174 offset:17152
	ds_read_b128 v[228:231], v174 offset:25600
	ds_read_b128 v[232:235], v174 offset:17216
	v_cvt_pk_bf16_f32 v72, v48, v49
	v_cvt_pk_bf16_f32 v73, v50, v51
	v_cvt_pk_bf16_f32 v74, v24, v25
	v_cvt_pk_bf16_f32 v75, v26, v27
	v_cvt_pk_bf16_f32 v76, v36, v37
	v_cvt_pk_bf16_f32 v77, v38, v39
	v_cvt_pk_bf16_f32 v78, v28, v29
	v_cvt_pk_bf16_f32 v79, v30, v31
	s_waitcnt lgkmcnt(11)
	s_nop 0
	v_mfma_f32_16x16x32_bf16 v[64:67], v[236:239], v[72:75], 0
	v_mfma_f32_16x16x32_bf16 v[68:71], v[250:253], v[72:75], 0
	v_mfma_f32_16x16x32_bf16 v[64:67], v[246:249], v[76:79], v[64:67]
	v_mfma_f32_16x16x32_bf16 v[68:71], v[100:103], v[76:79], v[68:71]
	ds_read2_b64 v[236:239], v175 offset0:16 offset1:20
	ds_read2_b64 v[250:253], v80 offset0:48 offset1:52
	ds_read2_b64 v[246:249], v175 offset0:24 offset1:28
	ds_read2_b64 v[100:103], v80 offset0:56 offset1:60
	s_waitcnt lgkmcnt(13)
	v_mfma_f32_16x16x4_f32 v[56:59], v190, v48, 0
	v_mfma_f32_16x16x4_f32 v[60:63], v194, v48, 0
	v_mfma_f32_16x16x4_f32 v[56:59], v191, v49, v[56:59]
	v_mfma_f32_16x16x4_f32 v[60:63], v195, v49, v[60:63]
	v_mfma_f32_16x16x4_f32 v[56:59], v192, v50, v[56:59]
	v_mfma_f32_16x16x4_f32 v[60:63], v196, v50, v[60:63]
	v_mfma_f32_16x16x4_f32 v[56:59], v193, v51, v[56:59]
	v_mfma_f32_16x16x4_f32 v[60:63], v197, v51, v[60:63]
	ds_read_b128 v[190:193], v174 offset:25664
	ds_read_b128 v[194:197], v174 offset:17280
	s_waitcnt lgkmcnt(13)
	v_mfma_f32_16x16x4_f32 v[56:59], v198, v24, v[56:59]
	v_mfma_f32_16x16x4_f32 v[60:63], v202, v24, v[60:63]
	v_mfma_f32_16x16x4_f32 v[56:59], v199, v25, v[56:59]
	v_mfma_f32_16x16x4_f32 v[60:63], v203, v25, v[60:63]
	v_mfma_f32_16x16x4_f32 v[56:59], v200, v26, v[56:59]
	v_mfma_f32_16x16x4_f32 v[60:63], v204, v26, v[60:63]
	v_mfma_f32_16x16x4_f32 v[56:59], v201, v27, v[56:59]
	v_mfma_f32_16x16x4_f32 v[60:63], v205, v27, v[60:63]
	ds_read_b128 v[198:201], v174 offset:25728
	ds_read_b128 v[202:205], v174 offset:17344
	s_waitcnt lgkmcnt(13)
	v_mfma_f32_16x16x4_f32 v[56:59], v208, v36, v[56:59]
	v_mfma_f32_16x16x4_f32 v[60:63], v212, v36, v[60:63]
	v_mfma_f32_16x16x4_f32 v[56:59], v209, v37, v[56:59]
	v_mfma_f32_16x16x4_f32 v[60:63], v213, v37, v[60:63]
	v_mfma_f32_16x16x4_f32 v[56:59], v210, v38, v[56:59]
	v_mfma_f32_16x16x4_f32 v[60:63], v214, v38, v[60:63]
	v_mfma_f32_16x16x4_f32 v[56:59], v211, v39, v[56:59]
	v_mfma_f32_16x16x4_f32 v[60:63], v215, v39, v[60:63]
	ds_read_b128 v[208:211], v174 offset:25792
	s_waitcnt lgkmcnt(12)
	v_mfma_f32_16x16x4_f32 v[56:59], v216, v28, v[56:59]
	v_mfma_f32_16x16x4_f32 v[60:63], v220, v28, v[60:63]
	v_mfma_f32_16x16x4_f32 v[56:59], v217, v29, v[56:59]
	v_mfma_f32_16x16x4_f32 v[60:63], v221, v29, v[60:63]
	v_mfma_f32_16x16x4_f32 v[56:59], v218, v30, v[56:59]
	v_mfma_f32_16x16x4_f32 v[60:63], v222, v30, v[60:63]
	v_mfma_f32_16x16x4_f32 v[56:59], v219, v31, v[56:59]
	v_mfma_f32_16x16x4_f32 v[60:63], v223, v31, v[60:63]
	v_cvt_pk_bf16_f32 v72, v40, v41
	v_cvt_pk_bf16_f32 v73, v42, v43
	v_cvt_pk_bf16_f32 v74, v32, v33
	v_cvt_pk_bf16_f32 v75, v34, v35
	v_cvt_pk_bf16_f32 v76, v44, v45
	v_cvt_pk_bf16_f32 v77, v46, v47
	v_cvt_pk_bf16_f32 v78, v52, v53
	v_cvt_pk_bf16_f32 v79, v54, v55
	s_waitcnt lgkmcnt(10)
	v_mfma_f32_16x16x4_f32 v[56:59], v224, v40, v[56:59]
	v_mfma_f32_16x16x4_f32 v[60:63], v228, v40, v[60:63]
	v_mfma_f32_16x16x4_f32 v[56:59], v225, v41, v[56:59]
	v_mfma_f32_16x16x4_f32 v[60:63], v229, v41, v[60:63]
	v_mfma_f32_16x16x4_f32 v[56:59], v226, v42, v[56:59]
	v_mfma_f32_16x16x4_f32 v[60:63], v230, v42, v[60:63]
	v_mfma_f32_16x16x4_f32 v[56:59], v227, v43, v[56:59]
	v_mfma_f32_16x16x4_f32 v[60:63], v231, v43, v[60:63]
	s_waitcnt lgkmcnt(4)
	v_mfma_f32_16x16x4_f32 v[56:59], v232, v32, v[56:59]
	v_mfma_f32_16x16x4_f32 v[60:63], v190, v32, v[60:63]
	v_mfma_f32_16x16x4_f32 v[56:59], v233, v33, v[56:59]
	v_mfma_f32_16x16x4_f32 v[60:63], v191, v33, v[60:63]
	v_mfma_f32_16x16x4_f32 v[56:59], v234, v34, v[56:59]
	v_mfma_f32_16x16x4_f32 v[60:63], v192, v34, v[60:63]
	v_mfma_f32_16x16x4_f32 v[56:59], v235, v35, v[56:59]
	v_mfma_f32_16x16x4_f32 v[60:63], v193, v35, v[60:63]
	s_waitcnt lgkmcnt(2)
	v_mfma_f32_16x16x4_f32 v[56:59], v194, v44, v[56:59]
	v_mfma_f32_16x16x4_f32 v[60:63], v198, v44, v[60:63]
	v_mfma_f32_16x16x4_f32 v[56:59], v195, v45, v[56:59]
	v_mfma_f32_16x16x4_f32 v[60:63], v199, v45, v[60:63]
	v_mfma_f32_16x16x4_f32 v[56:59], v196, v46, v[56:59]
	v_mfma_f32_16x16x4_f32 v[60:63], v200, v46, v[60:63]
	v_mfma_f32_16x16x4_f32 v[56:59], v197, v47, v[56:59]
	v_mfma_f32_16x16x4_f32 v[60:63], v201, v47, v[60:63]
	s_waitcnt lgkmcnt(0)
	v_mfma_f32_16x16x4_f32 v[56:59], v202, v52, v[56:59]
	v_mfma_f32_16x16x4_f32 v[60:63], v208, v52, v[60:63]
	v_mfma_f32_16x16x4_f32 v[56:59], v203, v53, v[56:59]
	v_mfma_f32_16x16x4_f32 v[60:63], v209, v53, v[60:63]
	v_mfma_f32_16x16x4_f32 v[56:59], v204, v54, v[56:59]
	v_mfma_f32_16x16x4_f32 v[60:63], v210, v54, v[60:63]
	v_mfma_f32_16x16x4_f32 v[56:59], v205, v55, v[56:59]
	v_mfma_f32_16x16x4_f32 v[60:63], v211, v55, v[60:63]
	v_mfma_f32_16x16x32_bf16 v[64:67], v[236:239], v[72:75], v[64:67]
	v_mfma_f32_16x16x32_bf16 v[68:71], v[250:253], v[72:75], v[68:71]
	v_mfma_f32_16x16x32_bf16 v[64:67], v[246:249], v[76:79], v[64:67]
	v_mfma_f32_16x16x32_bf16 v[68:71], v[100:103], v[76:79], v[68:71]

; #define LAS __attribute__((address_space(3)))
; DI void gdn_scan_block(LAS unsigned char* lds, int c, const float* P, const GdnPar& pr, float* ORAW, int tid, int lane, int wave) {
;     ...
;             const int gw4 = wave - 4, tb = gw4 & 1; const LAS unsigned char* XB = (gw4 >> 1) ? QB : KB; LAS float* OUT = (gw4 >> 1) ? HM : GM;
;             f32x4 acc[2] = {(f32x4){0.f, 0.f, 0.f, 0.f}, (f32x4){0.f, 0.f, 0.f, 0.f}};
; #pragma unroll
;             for (int ks = 0; ks < 4; ++ks) { const bf16x8 aX = *(const LAS bf16x8*)(XB + ((16 * tb + m) * 136 + 32 * ks + 8 * g) * 2);
; #pragma unroll
;                 for (int jb = 0; jb < 2; ++jb) acc[jb] = __builtin_amdgcn_mfma_f32_16x16x32_bf16(aX, *(const LAS bf16x8*)(KB + ((16 * jb + m) * 136 + 32 * ks + 8 * g) * 2), acc[jb], 0, 0, 0); }
; #pragma unroll
;             for (int jb = 0; jb < 2; ++jb)
; #pragma unroll
;                 for (int i = 0; i < 4; ++i) OUT[(16 * tb + 4 * g + i) * 33 + 16 * jb + m] = acc[jb][i];
;             if (wave == 4 && lane == 0) { float s = 0.f;
;                 for (int t = 0; t < 32; ++t) { s += AB_[2 * t]; GC_[t] = s; }
;                 for (int t = 0; t < 32; ++t) E31_[t] = __expf(s - GC_[t]); }
.LBB0_948:
	ds_read_b128 v[72:75], v164
	ds_read_b128 v[76:79], v165
	ds_read_b128 v[100:103], v166
	s_waitcnt lgkmcnt(1)
	v_mfma_f32_16x16x32_bf16 v[76:79], v[72:75], v[76:79], 0
	s_waitcnt lgkmcnt(0)
	v_mfma_f32_16x16x32_bf16 v[72:75], v[72:75], v[100:103], 0
	ds_read_b128 v[100:103], v164 offset:64
	ds_read_b128 v[190:193], v167
	s_waitcnt lgkmcnt(0)
	v_mfma_f32_16x16x32_bf16 v[76:79], v[100:103], v[190:193], v[76:79]
	ds_read_b128 v[190:193], v168
	s_waitcnt lgkmcnt(0)
	v_mfma_f32_16x16x32_bf16 v[72:75], v[100:103], v[190:193], v[72:75]
	ds_read_b128 v[100:103], v164 offset:128
	ds_read_b128 v[190:193], v169
	s_waitcnt lgkmcnt(0)
	v_mfma_f32_16x16x32_bf16 v[76:79], v[100:103], v[190:193], v[76:79]
	ds_read_b128 v[190:193], v170
	s_waitcnt lgkmcnt(0)
	v_mfma_f32_16x16x32_bf16 v[72:75], v[100:103], v[190:193], v[72:75]
	ds_read_b128 v[100:103], v164 offset:192
	ds_read_b128 v[190:193], v171
	s_waitcnt lgkmcnt(0)
	v_mfma_f32_16x16x32_bf16 v[76:79], v[100:103], v[190:193], v[76:79]
	ds_read_b128 v[190:193], v172
	s_waitcnt lgkmcnt(0)
	v_mfma_f32_16x16x32_bf16 v[72:75], v[100:103], v[190:193], v[72:75]
	s_nop 7
	ds_write2_b32 v173, v76, v72 offset1:16
	ds_write2_b32 v173, v77, v73 offset0:33 offset1:49
	ds_write2_b32 v173, v78, v74 offset0:66 offset1:82
	ds_write2_b32 v173, v79, v75 offset0:99 offset1:115
	s_and_saveexec_b64 s[34:35], s[72:73]
	s_cbranch_execz .LBB0_950
	s_mov_b32 exec_lo, -1
	s_mov_b32 exec_hi, 0
	v_lshl_add_u32 v72, v254, 3, s78
	v_lshl_add_u32 v73, v254, 2, s78
	ds_read_b32 v74, v72 offset:41984
	s_waitcnt lgkmcnt(0)
	s_nop 1
	v_add_f32_dpp v74, v74, v74 row_shr:1 row_mask:0xf bank_mask:0xf bound_ctrl:1
	s_nop 1
	v_add_f32_dpp v74, v74, v74 row_shr:2 row_mask:0xf bank_mask:0xf bound_ctrl:1
	s_nop 1
	v_add_f32_dpp v74, v74, v74 row_shr:4 row_mask:0xf bank_mask:0xf bound_ctrl:1
	s_nop 1
	v_add_f32_dpp v74, v74, v74 row_shr:8 row_mask:0xf bank_mask:0xf bound_ctrl:1
	s_nop 1
	v_add_f32_dpp v74, v74, v74 row_bcast:15 row_mask:0xa bank_mask:0xf
	s_nop 1
	v_readlane_b32 s98, v74, 31
	ds_write_b32 v73, v74 offset:42240
	s_nop 2
	v_sub_f32_e32 v75, s98, v74
	v_mul_f32_e32 v75, 0x3fb8aa3b, v75
	v_exp_f32_e32 v75, v75
	s_nop 0
	ds_write_b32 v73, v75 offset:42368
